# final-phase epilogue: the eight per-row-block atomics of the first pass deferred and issued together (loads no longer queue behind an atomic)
# baseline (speedup 1.0000x reference)
.LBB0_754:
	v_lshl_add_u32 v144, s66, 8, v186
	v_ashrrev_i32_e32 v145, 31, v144
	v_lshl_add_u64 v[154:155], v[144:145], 2, s[20:21]
	global_load_dword v168, v[154:155], off
	v_lshl_or_b32 v146, s42, 8, v188
	v_ashrrev_i32_e32 v147, 31, v146
	v_lshlrev_b64 v[148:149], 10, v[144:145]
	v_lshl_add_u64 v[148:149], v[148:149], 0, v[146:147]
	v_lshlrev_b64 v[152:153], 1, v[148:149]
	v_lshl_add_u64 v[148:149], s[8:9], 0, v[152:153]
	v_lshl_add_u64 v[156:157], s[18:19], 0, v[152:153]
	global_load_dwordx4 v[148:151], v[148:149], off
	v_and_b32_e32 v161, 64, v192
	global_load_dwordx4 v[156:159], v[156:157], off
	v_xor_b32_e32 v160, 16, v192
	v_add_u32_e32 v175, 64, v161
	v_cmp_lt_i32_e32 vcc, v160, v175
	v_or_b32_e32 v152, 0x100, v152
	s_waitcnt vmcnt(0)
	v_lshlrev_b32_e32 v170, 16, v150
	v_cndmask_b32_e32 v160, v192, v160, vcc
	v_lshlrev_b32_e32 v194, 2, v160
	v_lshl_add_u64 v[160:161], s[18:19], 0, v[152:153]
	v_lshl_add_u64 v[152:153], s[8:9], 0, v[152:153]
	global_load_dwordx4 v[160:163], v[160:161], off
	s_nop 0
	global_load_dwordx4 v[164:167], v[152:153], off
	v_fmamk_f32 v152, v168, 0x3a800000, v193
	v_rsq_f32_e32 v174, v152
	v_lshlrev_b32_e32 v152, 16, v148
	v_and_b32_e32 v153, 0xffff0000, v148
	v_lshlrev_b32_e32 v168, 16, v156
	v_mul_f32_e32 v174, 0xbfb8aa3b, v174
	v_pk_mul_f32 v[126:127], v[126:127], v[174:175] op_sel_hi:[1,0]
	v_pk_mul_f32 v[124:125], v[124:125], v[174:175] op_sel_hi:[1,0]
	v_pk_mul_f32 v[122:123], v[122:123], v[174:175] op_sel_hi:[1,0]
	v_pk_mul_f32 v[120:121], v[120:121], v[174:175] op_sel_hi:[1,0]
	v_pk_mul_f32 v[176:177], v[114:115], v[174:175] op_sel_hi:[1,0]
	v_exp_f32_e32 v114, v124
	v_exp_f32_e32 v115, v125
	v_exp_f32_e32 v124, v126
	v_exp_f32_e32 v125, v127
	v_pk_mul_f32 v[116:117], v[116:117], v[174:175] op_sel_hi:[1,0]
	v_exp_f32_e32 v120, v120
	v_exp_f32_e32 v121, v121
	v_exp_f32_e32 v122, v122
	v_exp_f32_e32 v123, v123
	v_exp_f32_e32 v116, v116
	v_exp_f32_e32 v117, v117
	v_pk_mul_f32 v[118:119], v[118:119], v[174:175] op_sel_hi:[1,0]
	v_pk_mul_f32 v[112:113], v[112:113], v[174:175] op_sel_hi:[1,0]
	v_exp_f32_e32 v118, v118
	v_exp_f32_e32 v119, v119
	v_exp_f32_e32 v174, v112
	v_exp_f32_e32 v178, v113
	v_add_f32_e32 v112, 1.0, v114
	v_add_f32_e32 v113, 1.0, v115
	v_add_f32_e32 v114, 1.0, v124
	v_add_f32_e32 v115, 1.0, v125
	v_add_f32_e32 v120, 1.0, v120
	v_add_f32_e32 v121, 1.0, v121
	v_add_f32_e32 v122, 1.0, v122
	v_add_f32_e32 v123, 1.0, v123
	v_rcp_f32_e32 v112, v112
	v_rcp_f32_e32 v113, v113
	v_rcp_f32_e32 v114, v114
	v_rcp_f32_e32 v115, v115
	v_add_f32_e32 v124, 1.0, v116
	v_add_f32_e32 v125, 1.0, v117
	v_rcp_f32_e32 v116, v120
	v_rcp_f32_e32 v117, v121
	v_rcp_f32_e32 v122, v122
	v_rcp_f32_e32 v123, v123
	v_and_b32_e32 v169, 0xffff0000, v156
	v_lshlrev_b32_e32 v148, 16, v149
	v_and_b32_e32 v149, 0xffff0000, v149
	v_lshlrev_b32_e32 v156, 16, v157
	v_and_b32_e32 v157, 0xffff0000, v157
	v_add_f32_e32 v118, 1.0, v118
	v_add_f32_e32 v119, 1.0, v119
	v_and_b32_e32 v171, 0xffff0000, v150
	v_lshlrev_b32_e32 v172, 16, v158
	v_and_b32_e32 v173, 0xffff0000, v158
	v_lshlrev_b32_e32 v150, 16, v151
	v_and_b32_e32 v151, 0xffff0000, v151
	v_lshlrev_b32_e32 v158, 16, v159
	v_and_b32_e32 v159, 0xffff0000, v159
	v_rcp_f32_e32 v126, v118
	v_rcp_f32_e32 v127, v119
	v_pk_fma_f32 v[120:121], v[112:113], v[168:169], v[152:153]
	v_pk_fma_f32 v[118:119], v[114:115], v[156:157], v[148:149]
	v_pk_fma_f32 v[116:117], v[116:117], v[172:173], v[170:171]
	v_pk_fma_f32 v[114:115], v[122:123], v[158:159], v[150:151]
	v_pk_mul_f32 v[112:113], v[118:119], v[118:119]
	v_pk_mul_f32 v[122:123], v[120:121], v[120:121]
	v_pk_mul_f32 v[148:149], v[114:115], v[114:115]
	v_pk_mul_f32 v[150:151], v[116:117], v[116:117]
	v_add_f32_e32 v122, v122, v123
	v_add_f32_e32 v112, v112, v113
	v_add_f32_e32 v113, v150, v151
	v_add_f32_e32 v123, v148, v149
	v_add_f32_e32 v112, v122, v112
	v_exp_f32_e32 v122, v176
	v_add_f32_e32 v113, v113, v123
	v_exp_f32_e32 v123, v177
	v_rcp_f32_e32 v124, v124
	v_rcp_f32_e32 v125, v125
	v_add_f32_e32 v158, v112, v113
	v_add_f32_e32 v112, 1.0, v174
	v_add_f32_e32 v113, 1.0, v178
	v_add_f32_e32 v122, 1.0, v122
	v_rcp_f32_e32 v112, v112
	v_rcp_f32_e32 v113, v113
	v_rcp_f32_e32 v148, v122
	v_add_f32_e32 v122, 1.0, v123
	v_rcp_f32_e32 v149, v122
	s_waitcnt vmcnt(0)
	v_lshlrev_b32_e32 v122, 16, v164
	v_and_b32_e32 v123, 0xffff0000, v164
	v_lshlrev_b32_e32 v150, 16, v160
	v_and_b32_e32 v151, 0xffff0000, v160
	v_pk_fma_f32 v[122:123], v[124:125], v[150:151], v[122:123]
	v_lshlrev_b32_e32 v124, 16, v165
	v_and_b32_e32 v125, 0xffff0000, v165
	v_lshlrev_b32_e32 v150, 16, v161
	v_and_b32_e32 v151, 0xffff0000, v161
	v_pk_fma_f32 v[124:125], v[126:127], v[150:151], v[124:125]
	v_lshlrev_b32_e32 v126, 16, v166
	v_and_b32_e32 v127, 0xffff0000, v166
	v_lshlrev_b32_e32 v150, 16, v162
	v_and_b32_e32 v151, 0xffff0000, v162
	v_pk_fma_f32 v[126:127], v[112:113], v[150:151], v[126:127]
	v_lshlrev_b32_e32 v112, 16, v167
	v_and_b32_e32 v113, 0xffff0000, v167
	v_lshlrev_b32_e32 v150, 16, v163
	v_and_b32_e32 v151, 0xffff0000, v163
	v_pk_fma_f32 v[148:149], v[148:149], v[150:151], v[112:113]
	v_pk_mul_f32 v[112:113], v[124:125], v[124:125]
	v_pk_mul_f32 v[150:151], v[122:123], v[122:123]
	v_pk_mul_f32 v[152:153], v[148:149], v[148:149]
	v_pk_mul_f32 v[156:157], v[126:127], v[126:127]
	v_add_f32_e32 v150, v150, v151
	v_add_f32_e32 v112, v112, v113
	v_add_f32_e32 v112, v150, v112
	v_add_f32_e32 v113, v156, v157
	v_add_f32_e32 v150, v152, v153
	v_add_f32_e32 v113, v113, v150
	v_add_f32_e32 v112, v112, v113
	v_add_f32_e32 v112, v158, v112
	ds_bpermute_b32 v113, v194, v112
	v_xor_b32_e32 v150, 32, v192
	v_cmp_lt_i32_e32 vcc, v150, v175
	s_nop 1
	v_cndmask_b32_e32 v150, v192, v150, vcc
	v_lshlrev_b32_e32 v195, 2, v150
	s_waitcnt lgkmcnt(0)
	v_add_f32_e32 v150, v112, v113
	ds_bpermute_b32 v151, v195, v150
	v_lshl_add_u64 v[112:113], v[144:145], 2, s[22:23]
	s_and_saveexec_b64 s[42:43], s[0:1]
	s_cbranch_execz .LBB0_756
	s_waitcnt lgkmcnt(0)
	v_add_f32_e32 v150, v150, v151
	v_mov_b32_e32 v226, v150
	v_mov_b32_e32 v234, v112
	v_mov_b32_e32 v235, v113
.LBB0_756:
	s_or_b64 exec, exec, s[42:43]
	v_or_b32_e32 v150, 16, v144
	s_waitcnt lgkmcnt(0)
	v_ashrrev_i32_e32 v151, 31, v150
	v_lshl_add_u64 v[152:153], v[150:151], 2, s[20:21]
	global_load_dword v172, v[152:153], off
	v_lshlrev_b64 v[152:153], 10, v[150:151]
	v_lshl_add_u64 v[152:153], v[152:153], 0, v[146:147]
	v_lshlrev_b64 v[152:153], 1, v[152:153]
	v_lshl_add_u64 v[156:157], s[8:9], 0, v[152:153]
	v_lshl_add_u64 v[160:161], s[18:19], 0, v[152:153]
	global_load_dwordx4 v[156:159], v[156:157], off
	v_or_b32_e32 v152, 0x100, v152
	global_load_dwordx4 v[160:163], v[160:161], off
	v_lshl_add_u64 v[164:165], s[18:19], 0, v[152:153]
	v_lshl_add_u64 v[152:153], s[8:9], 0, v[152:153]
	global_load_dwordx4 v[164:167], v[164:165], off
	s_nop 0
	global_load_dwordx4 v[168:171], v[152:153], off
	s_waitcnt vmcnt(4)
	v_fmamk_f32 v152, v172, 0x3a800000, v193
	v_rsq_f32_e32 v178, v152
	s_waitcnt vmcnt(3)
	v_lshlrev_b32_e32 v152, 16, v156
	v_mul_f32_e32 v178, 0xbfb8aa3b, v178
	v_pk_mul_f32 v[110:111], v[110:111], v[178:179] op_sel_hi:[1,0]
	v_pk_mul_f32 v[108:109], v[108:109], v[178:179] op_sel_hi:[1,0]
	v_pk_mul_f32 v[106:107], v[106:107], v[178:179] op_sel_hi:[1,0]
	v_pk_mul_f32 v[104:105], v[104:105], v[178:179] op_sel_hi:[1,0]
	v_pk_mul_f32 v[98:99], v[98:99], v[178:179] op_sel_hi:[1,0]
	v_pk_mul_f32 v[96:97], v[96:97], v[178:179] op_sel_hi:[1,0]
	v_exp_f32_e32 v108, v108
	v_exp_f32_e32 v109, v109
	v_exp_f32_e32 v110, v110
	v_exp_f32_e32 v111, v111
	v_exp_f32_e32 v104, v104
	v_exp_f32_e32 v105, v105
	v_exp_f32_e32 v106, v106
	v_exp_f32_e32 v107, v107
	v_exp_f32_e32 v96, v96
	v_exp_f32_e32 v97, v97
	v_exp_f32_e32 v98, v98
	v_pk_mul_f32 v[102:103], v[102:103], v[178:179] op_sel_hi:[1,0]
	v_pk_mul_f32 v[100:101], v[100:101], v[178:179] op_sel_hi:[1,0]
	v_exp_f32_e32 v102, v102
	v_exp_f32_e32 v100, v100
	v_exp_f32_e32 v101, v101
	v_exp_f32_e32 v103, v103
	v_exp_f32_e32 v181, v99
	v_add_f32_e32 v99, 1.0, v108
	v_add_f32_e32 v108, 1.0, v109
	v_add_f32_e32 v109, 1.0, v110
	v_add_f32_e32 v110, 1.0, v111
	v_add_f32_e32 v104, 1.0, v104
	v_add_f32_e32 v105, 1.0, v105
	v_add_f32_e32 v106, 1.0, v106
	v_add_f32_e32 v107, 1.0, v107
	v_add_f32_e32 v178, 1.0, v96
	v_add_f32_e32 v179, 1.0, v97
	v_add_f32_e32 v180, 1.0, v98
	v_rcp_f32_e32 v96, v99
	v_rcp_f32_e32 v97, v108
	v_rcp_f32_e32 v98, v109
	v_rcp_f32_e32 v99, v110
	v_rcp_f32_e32 v104, v104
	v_rcp_f32_e32 v105, v105
	v_rcp_f32_e32 v106, v106
	v_rcp_f32_e32 v107, v107
	v_and_b32_e32 v153, 0xffff0000, v156
	s_waitcnt vmcnt(2)
	v_lshlrev_b32_e32 v172, 16, v160
	v_and_b32_e32 v173, 0xffff0000, v160
	v_lshlrev_b32_e32 v156, 16, v157
	v_and_b32_e32 v157, 0xffff0000, v157
	v_lshlrev_b32_e32 v160, 16, v161
	v_and_b32_e32 v161, 0xffff0000, v161
	v_lshlrev_b32_e32 v174, 16, v158
	v_and_b32_e32 v175, 0xffff0000, v158
	v_lshlrev_b32_e32 v176, 16, v162
	v_and_b32_e32 v177, 0xffff0000, v162
	v_lshlrev_b32_e32 v158, 16, v159
	v_and_b32_e32 v159, 0xffff0000, v159
	v_lshlrev_b32_e32 v162, 16, v163
	v_and_b32_e32 v163, 0xffff0000, v163
	v_add_f32_e32 v100, 1.0, v100
	v_add_f32_e32 v101, 1.0, v101
	v_add_f32_e32 v102, 1.0, v102
	v_add_f32_e32 v103, 1.0, v103
	v_rcp_f32_e32 v108, v100
	v_rcp_f32_e32 v109, v101
	v_rcp_f32_e32 v110, v102
	v_rcp_f32_e32 v111, v103
	v_pk_fma_f32 v[102:103], v[96:97], v[172:173], v[152:153]
	v_pk_fma_f32 v[100:101], v[98:99], v[160:161], v[156:157]
	v_pk_fma_f32 v[98:99], v[104:105], v[176:177], v[174:175]
	v_pk_fma_f32 v[96:97], v[106:107], v[162:163], v[158:159]
	v_pk_mul_f32 v[104:105], v[100:101], v[100:101]
	v_pk_mul_f32 v[106:107], v[102:103], v[102:103]
	v_pk_mul_f32 v[152:153], v[96:97], v[96:97]
	v_pk_mul_f32 v[156:157], v[98:99], v[98:99]
	v_add_f32_e32 v106, v106, v107
	v_add_f32_e32 v104, v104, v105
	v_add_f32_e32 v105, v156, v157
	v_add_f32_e32 v107, v152, v153
	v_add_f32_e32 v104, v106, v104
	v_add_f32_e32 v105, v105, v107
	v_rcp_f32_e32 v178, v178
	v_rcp_f32_e32 v179, v179
	v_add_f32_e32 v162, v104, v105
	v_add_f32_e32 v104, 1.0, v181
	v_rcp_f32_e32 v180, v180
	v_rcp_f32_e32 v181, v104
	s_waitcnt vmcnt(0)
	v_lshlrev_b32_e32 v104, 16, v168
	v_and_b32_e32 v105, 0xffff0000, v168
	v_lshlrev_b32_e32 v106, 16, v164
	v_and_b32_e32 v107, 0xffff0000, v164
	v_pk_fma_f32 v[104:105], v[108:109], v[106:107], v[104:105]
	v_lshlrev_b32_e32 v106, 16, v169
	v_and_b32_e32 v107, 0xffff0000, v169
	v_lshlrev_b32_e32 v108, 16, v165
	v_and_b32_e32 v109, 0xffff0000, v165
	v_pk_fma_f32 v[106:107], v[110:111], v[108:109], v[106:107]
	v_lshlrev_b32_e32 v108, 16, v170
	v_and_b32_e32 v109, 0xffff0000, v170
	v_lshlrev_b32_e32 v110, 16, v166
	v_and_b32_e32 v111, 0xffff0000, v166
	v_pk_fma_f32 v[108:109], v[178:179], v[110:111], v[108:109]
	v_lshlrev_b32_e32 v110, 16, v171
	v_and_b32_e32 v111, 0xffff0000, v171
	v_lshlrev_b32_e32 v152, 16, v167
	v_and_b32_e32 v153, 0xffff0000, v167
	v_pk_fma_f32 v[110:111], v[180:181], v[152:153], v[110:111]
	v_pk_mul_f32 v[152:153], v[106:107], v[106:107]
	v_pk_mul_f32 v[156:157], v[104:105], v[104:105]
	v_pk_mul_f32 v[158:159], v[110:111], v[110:111]
	v_pk_mul_f32 v[160:161], v[108:109], v[108:109]
	v_add_f32_e32 v156, v156, v157
	v_add_f32_e32 v152, v152, v153
	v_add_f32_e32 v152, v156, v152
	v_add_f32_e32 v153, v160, v161
	v_add_f32_e32 v156, v158, v159
	v_add_f32_e32 v153, v153, v156
	v_add_f32_e32 v152, v152, v153
	v_add_f32_e32 v152, v162, v152
	ds_bpermute_b32 v153, v194, v152
	v_lshl_add_u64 v[156:157], v[150:151], 2, s[22:23]
	s_waitcnt lgkmcnt(0)
	v_add_f32_e32 v152, v152, v153
	ds_bpermute_b32 v153, v195, v152
	s_and_saveexec_b64 s[42:43], s[0:1]
	s_cbranch_execz .LBB0_758
	s_waitcnt lgkmcnt(0)
	v_add_f32_e32 v152, v152, v153
	v_mov_b32_e32 v227, v152
.LBB0_758:
	s_or_b64 exec, exec, s[42:43]
	v_or_b32_e32 v152, 32, v144
	s_waitcnt lgkmcnt(0)
	v_ashrrev_i32_e32 v153, 31, v152
	v_lshl_add_u64 v[158:159], v[152:153], 2, s[20:21]
	global_load_dword v174, v[158:159], off
	v_lshlrev_b64 v[158:159], 10, v[152:153]
	v_lshl_add_u64 v[158:159], v[158:159], 0, v[146:147]
	v_lshlrev_b64 v[166:167], 1, v[158:159]
	v_lshl_add_u64 v[158:159], s[8:9], 0, v[166:167]
	v_lshl_add_u64 v[162:163], s[18:19], 0, v[166:167]
	global_load_dwordx4 v[158:161], v[158:159], off
	v_or_b32_e32 v166, 0x100, v166
	global_load_dwordx4 v[162:165], v[162:163], off
	v_lshl_add_u64 v[168:169], s[18:19], 0, v[166:167]
	v_lshl_add_u64 v[170:171], s[8:9], 0, v[166:167]
	global_load_dwordx4 v[166:169], v[168:169], off
	s_nop 0
	global_load_dwordx4 v[170:173], v[170:171], off
	s_waitcnt vmcnt(4)
	v_fmamk_f32 v174, v174, 0x3a800000, v193
	v_rsq_f32_e32 v182, v174
	s_waitcnt vmcnt(3)
	v_lshlrev_b32_e32 v174, 16, v158
	v_mul_f32_e32 v182, 0xbfb8aa3b, v182
	v_pk_mul_f32 v[94:95], v[94:95], v[182:183] op_sel_hi:[1,0]
	v_pk_mul_f32 v[92:93], v[92:93], v[182:183] op_sel_hi:[1,0]
	v_pk_mul_f32 v[90:91], v[90:91], v[182:183] op_sel_hi:[1,0]
	v_pk_mul_f32 v[88:89], v[88:89], v[182:183] op_sel_hi:[1,0]
	v_pk_mul_f32 v[82:83], v[82:83], v[182:183] op_sel_hi:[1,0]
	v_pk_mul_f32 v[80:81], v[80:81], v[182:183] op_sel_hi:[1,0]
	v_exp_f32_e32 v92, v92
	v_exp_f32_e32 v93, v93
	v_exp_f32_e32 v94, v94
	v_exp_f32_e32 v95, v95
	v_exp_f32_e32 v88, v88
	v_exp_f32_e32 v89, v89
	v_exp_f32_e32 v90, v90
	v_exp_f32_e32 v91, v91
	v_exp_f32_e32 v80, v80
	v_exp_f32_e32 v81, v81
	v_exp_f32_e32 v82, v82
	v_pk_mul_f32 v[86:87], v[86:87], v[182:183] op_sel_hi:[1,0]
	v_pk_mul_f32 v[84:85], v[84:85], v[182:183] op_sel_hi:[1,0]
	v_exp_f32_e32 v86, v86
	v_exp_f32_e32 v84, v84
	v_exp_f32_e32 v85, v85
	v_exp_f32_e32 v87, v87
	v_exp_f32_e32 v185, v83
	v_add_f32_e32 v83, 1.0, v92
	v_add_f32_e32 v92, 1.0, v93
	v_add_f32_e32 v93, 1.0, v94
	v_add_f32_e32 v94, 1.0, v95
	v_add_f32_e32 v88, 1.0, v88
	v_add_f32_e32 v89, 1.0, v89
	v_add_f32_e32 v90, 1.0, v90
	v_add_f32_e32 v91, 1.0, v91
	v_add_f32_e32 v182, 1.0, v80
	v_add_f32_e32 v183, 1.0, v81
	v_add_f32_e32 v184, 1.0, v82
	v_rcp_f32_e32 v80, v83
	v_rcp_f32_e32 v81, v92
	v_rcp_f32_e32 v82, v93
	v_rcp_f32_e32 v83, v94
	v_rcp_f32_e32 v88, v88
	v_rcp_f32_e32 v89, v89
	v_rcp_f32_e32 v90, v90
	v_rcp_f32_e32 v91, v91
	v_and_b32_e32 v175, 0xffff0000, v158
	s_waitcnt vmcnt(2)
	v_lshlrev_b32_e32 v176, 16, v162
	v_and_b32_e32 v177, 0xffff0000, v162
	v_lshlrev_b32_e32 v158, 16, v159
	v_and_b32_e32 v159, 0xffff0000, v159
	v_lshlrev_b32_e32 v162, 16, v163
	v_and_b32_e32 v163, 0xffff0000, v163
	v_lshlrev_b32_e32 v178, 16, v160
	v_and_b32_e32 v179, 0xffff0000, v160
	v_lshlrev_b32_e32 v180, 16, v164
	v_and_b32_e32 v181, 0xffff0000, v164
	v_lshlrev_b32_e32 v160, 16, v161
	v_and_b32_e32 v161, 0xffff0000, v161
	v_lshlrev_b32_e32 v164, 16, v165
	v_and_b32_e32 v165, 0xffff0000, v165
	v_add_f32_e32 v84, 1.0, v84
	v_add_f32_e32 v85, 1.0, v85
	v_add_f32_e32 v86, 1.0, v86
	v_add_f32_e32 v87, 1.0, v87
	v_rcp_f32_e32 v92, v84
	v_rcp_f32_e32 v93, v85
	v_rcp_f32_e32 v94, v86
	v_rcp_f32_e32 v95, v87
	v_pk_fma_f32 v[86:87], v[80:81], v[176:177], v[174:175]
	v_pk_fma_f32 v[84:85], v[82:83], v[162:163], v[158:159]
	v_pk_fma_f32 v[82:83], v[88:89], v[180:181], v[178:179]
	v_pk_fma_f32 v[80:81], v[90:91], v[164:165], v[160:161]
	v_pk_mul_f32 v[88:89], v[84:85], v[84:85]
	v_pk_mul_f32 v[90:91], v[86:87], v[86:87]
	v_pk_mul_f32 v[158:159], v[80:81], v[80:81]
	v_pk_mul_f32 v[160:161], v[82:83], v[82:83]
	v_add_f32_e32 v90, v90, v91
	v_add_f32_e32 v88, v88, v89
	v_add_f32_e32 v89, v160, v161
	v_add_f32_e32 v91, v158, v159
	v_add_f32_e32 v88, v90, v88
	v_add_f32_e32 v89, v89, v91
	v_rcp_f32_e32 v182, v182
	v_rcp_f32_e32 v183, v183
	v_add_f32_e32 v174, v88, v89
	v_add_f32_e32 v88, 1.0, v185
	v_rcp_f32_e32 v184, v184
	v_rcp_f32_e32 v185, v88
	s_waitcnt vmcnt(0)
	v_lshlrev_b32_e32 v88, 16, v170
	v_and_b32_e32 v89, 0xffff0000, v170
	v_lshlrev_b32_e32 v90, 16, v166
	v_and_b32_e32 v91, 0xffff0000, v166
	v_pk_fma_f32 v[88:89], v[92:93], v[90:91], v[88:89]
	v_lshlrev_b32_e32 v90, 16, v171
	v_and_b32_e32 v91, 0xffff0000, v171
	v_lshlrev_b32_e32 v92, 16, v167
	v_and_b32_e32 v93, 0xffff0000, v167
	v_pk_fma_f32 v[90:91], v[94:95], v[92:93], v[90:91]
	v_lshlrev_b32_e32 v92, 16, v172
	v_and_b32_e32 v93, 0xffff0000, v172
	v_lshlrev_b32_e32 v94, 16, v168
	v_and_b32_e32 v95, 0xffff0000, v168
	v_pk_fma_f32 v[92:93], v[182:183], v[94:95], v[92:93]
	v_lshlrev_b32_e32 v94, 16, v173
	v_and_b32_e32 v95, 0xffff0000, v173
	v_lshlrev_b32_e32 v158, 16, v169
	v_and_b32_e32 v159, 0xffff0000, v169
	v_pk_fma_f32 v[94:95], v[184:185], v[158:159], v[94:95]
	v_pk_mul_f32 v[158:159], v[90:91], v[90:91]
	v_pk_mul_f32 v[160:161], v[88:89], v[88:89]
	v_pk_mul_f32 v[162:163], v[94:95], v[94:95]
	v_pk_mul_f32 v[164:165], v[92:93], v[92:93]
	v_add_f32_e32 v160, v160, v161
	v_add_f32_e32 v158, v158, v159
	v_add_f32_e32 v158, v160, v158
	v_add_f32_e32 v159, v164, v165
	v_add_f32_e32 v160, v162, v163
	v_add_f32_e32 v159, v159, v160
	v_add_f32_e32 v158, v158, v159
	v_add_f32_e32 v158, v174, v158
	ds_bpermute_b32 v159, v194, v158
	v_lshl_add_u64 v[160:161], v[152:153], 2, s[22:23]
	s_waitcnt lgkmcnt(0)
	v_add_f32_e32 v158, v158, v159
	ds_bpermute_b32 v159, v195, v158
	s_and_saveexec_b64 s[42:43], s[0:1]
	s_cbranch_execz .LBB0_760
	s_waitcnt lgkmcnt(0)
	v_add_f32_e32 v158, v158, v159
	v_mov_b32_e32 v228, v158
.LBB0_760:
	s_or_b64 exec, exec, s[42:43]
	v_or_b32_e32 v158, 48, v144
	s_waitcnt lgkmcnt(0)
	v_ashrrev_i32_e32 v159, 31, v158
	v_lshl_add_u64 v[162:163], v[158:159], 2, s[20:21]
	global_load_dword v178, v[162:163], off
	v_lshlrev_b64 v[162:163], 10, v[158:159]
	v_lshl_add_u64 v[162:163], v[162:163], 0, v[146:147]
	v_lshlrev_b64 v[170:171], 1, v[162:163]
	v_lshl_add_u64 v[162:163], s[8:9], 0, v[170:171]
	v_lshl_add_u64 v[166:167], s[18:19], 0, v[170:171]
	global_load_dwordx4 v[162:165], v[162:163], off
	v_or_b32_e32 v170, 0x100, v170
	global_load_dwordx4 v[166:169], v[166:167], off
	v_lshl_add_u64 v[172:173], s[18:19], 0, v[170:171]
	v_lshl_add_u64 v[174:175], s[8:9], 0, v[170:171]
	global_load_dwordx4 v[170:173], v[172:173], off
	s_nop 0
	global_load_dwordx4 v[174:177], v[174:175], off
	s_waitcnt vmcnt(4)
	v_fmamk_f32 v178, v178, 0x3a800000, v193
	v_rsq_f32_e32 v196, v178
	s_waitcnt vmcnt(3)
	v_lshlrev_b32_e32 v178, 16, v162
	v_mul_f32_e32 v196, 0xbfb8aa3b, v196
	v_pk_mul_f32 v[78:79], v[78:79], v[196:197] op_sel_hi:[1,0]
	v_pk_mul_f32 v[76:77], v[76:77], v[196:197] op_sel_hi:[1,0]
	v_pk_mul_f32 v[74:75], v[74:75], v[196:197] op_sel_hi:[1,0]
	v_pk_mul_f32 v[72:73], v[72:73], v[196:197] op_sel_hi:[1,0]
	v_pk_mul_f32 v[66:67], v[66:67], v[196:197] op_sel_hi:[1,0]
	v_pk_mul_f32 v[64:65], v[64:65], v[196:197] op_sel_hi:[1,0]
	v_exp_f32_e32 v76, v76
	v_exp_f32_e32 v77, v77
	v_exp_f32_e32 v78, v78
	v_exp_f32_e32 v79, v79
	v_exp_f32_e32 v72, v72
	v_exp_f32_e32 v73, v73
	v_exp_f32_e32 v74, v74
	v_exp_f32_e32 v75, v75
	v_exp_f32_e32 v64, v64
	v_exp_f32_e32 v65, v65
	v_exp_f32_e32 v66, v66
	v_pk_mul_f32 v[70:71], v[70:71], v[196:197] op_sel_hi:[1,0]
	v_pk_mul_f32 v[68:69], v[68:69], v[196:197] op_sel_hi:[1,0]
	v_exp_f32_e32 v70, v70
	v_exp_f32_e32 v68, v68
	v_exp_f32_e32 v69, v69
	v_exp_f32_e32 v71, v71
	v_exp_f32_e32 v199, v67
	v_add_f32_e32 v67, 1.0, v76
	v_add_f32_e32 v76, 1.0, v77
	v_add_f32_e32 v77, 1.0, v78
	v_add_f32_e32 v78, 1.0, v79
	v_add_f32_e32 v72, 1.0, v72
	v_add_f32_e32 v73, 1.0, v73
	v_add_f32_e32 v74, 1.0, v74
	v_add_f32_e32 v75, 1.0, v75
	v_add_f32_e32 v196, 1.0, v64
	v_add_f32_e32 v197, 1.0, v65
	v_add_f32_e32 v198, 1.0, v66
	v_rcp_f32_e32 v64, v67
	v_rcp_f32_e32 v65, v76
	v_rcp_f32_e32 v66, v77
	v_rcp_f32_e32 v67, v78
	v_rcp_f32_e32 v72, v72
	v_rcp_f32_e32 v73, v73
	v_rcp_f32_e32 v74, v74
	v_rcp_f32_e32 v75, v75
	v_and_b32_e32 v179, 0xffff0000, v162
	s_waitcnt vmcnt(2)
	v_lshlrev_b32_e32 v180, 16, v166
	v_and_b32_e32 v181, 0xffff0000, v166
	v_lshlrev_b32_e32 v162, 16, v163
	v_and_b32_e32 v163, 0xffff0000, v163
	v_lshlrev_b32_e32 v166, 16, v167
	v_and_b32_e32 v167, 0xffff0000, v167
	v_lshlrev_b32_e32 v182, 16, v164
	v_and_b32_e32 v183, 0xffff0000, v164
	v_lshlrev_b32_e32 v184, 16, v168
	v_and_b32_e32 v185, 0xffff0000, v168
	v_lshlrev_b32_e32 v164, 16, v165
	v_and_b32_e32 v165, 0xffff0000, v165
	v_lshlrev_b32_e32 v168, 16, v169
	v_and_b32_e32 v169, 0xffff0000, v169
	v_add_f32_e32 v68, 1.0, v68
	v_add_f32_e32 v69, 1.0, v69
	v_add_f32_e32 v70, 1.0, v70
	v_add_f32_e32 v71, 1.0, v71
	v_rcp_f32_e32 v76, v68
	v_rcp_f32_e32 v77, v69
	v_rcp_f32_e32 v78, v70
	v_rcp_f32_e32 v79, v71
	v_pk_fma_f32 v[70:71], v[64:65], v[180:181], v[178:179]
	v_pk_fma_f32 v[68:69], v[66:67], v[166:167], v[162:163]
	v_pk_fma_f32 v[66:67], v[72:73], v[184:185], v[182:183]
	v_pk_fma_f32 v[64:65], v[74:75], v[168:169], v[164:165]
	v_pk_mul_f32 v[72:73], v[68:69], v[68:69]
	v_pk_mul_f32 v[74:75], v[70:71], v[70:71]
	v_pk_mul_f32 v[162:163], v[64:65], v[64:65]
	v_pk_mul_f32 v[164:165], v[66:67], v[66:67]
	v_add_f32_e32 v74, v74, v75
	v_add_f32_e32 v72, v72, v73
	v_add_f32_e32 v73, v164, v165
	v_add_f32_e32 v75, v162, v163
	v_add_f32_e32 v72, v74, v72
	v_add_f32_e32 v73, v73, v75
	v_rcp_f32_e32 v196, v196
	v_rcp_f32_e32 v197, v197
	v_add_f32_e32 v178, v72, v73
	v_add_f32_e32 v72, 1.0, v199
	v_rcp_f32_e32 v198, v198
	v_rcp_f32_e32 v199, v72
	s_waitcnt vmcnt(0)
	v_lshlrev_b32_e32 v72, 16, v174
	v_and_b32_e32 v73, 0xffff0000, v174
	v_lshlrev_b32_e32 v74, 16, v170
	v_and_b32_e32 v75, 0xffff0000, v170
	v_pk_fma_f32 v[72:73], v[76:77], v[74:75], v[72:73]
	v_lshlrev_b32_e32 v74, 16, v175
	v_and_b32_e32 v75, 0xffff0000, v175
	v_lshlrev_b32_e32 v76, 16, v171
	v_and_b32_e32 v77, 0xffff0000, v171
	v_pk_fma_f32 v[74:75], v[78:79], v[76:77], v[74:75]
	v_lshlrev_b32_e32 v76, 16, v176
	v_and_b32_e32 v77, 0xffff0000, v176
	v_lshlrev_b32_e32 v78, 16, v172
	v_and_b32_e32 v79, 0xffff0000, v172
	v_pk_fma_f32 v[76:77], v[196:197], v[78:79], v[76:77]
	v_lshlrev_b32_e32 v78, 16, v177
	v_and_b32_e32 v79, 0xffff0000, v177
	v_lshlrev_b32_e32 v162, 16, v173
	v_and_b32_e32 v163, 0xffff0000, v173
	v_pk_fma_f32 v[78:79], v[198:199], v[162:163], v[78:79]
	v_pk_mul_f32 v[162:163], v[74:75], v[74:75]
	v_pk_mul_f32 v[164:165], v[72:73], v[72:73]
	v_pk_mul_f32 v[166:167], v[78:79], v[78:79]
	v_pk_mul_f32 v[168:169], v[76:77], v[76:77]
	v_add_f32_e32 v164, v164, v165
	v_add_f32_e32 v162, v162, v163
	v_add_f32_e32 v162, v164, v162
	v_add_f32_e32 v163, v168, v169
	v_add_f32_e32 v164, v166, v167
	v_add_f32_e32 v163, v163, v164
	v_add_f32_e32 v162, v162, v163
	v_add_f32_e32 v162, v178, v162
	ds_bpermute_b32 v163, v194, v162
	v_lshl_add_u64 v[164:165], v[158:159], 2, s[22:23]
	s_waitcnt lgkmcnt(0)
	v_add_f32_e32 v162, v162, v163
	ds_bpermute_b32 v163, v195, v162
	s_and_saveexec_b64 s[42:43], s[0:1]
	s_cbranch_execz .LBB0_762
	s_waitcnt lgkmcnt(0)
	v_add_f32_e32 v162, v162, v163
	v_mov_b32_e32 v229, v162
.LBB0_762:
	s_or_b64 exec, exec, s[42:43]
	global_load_dword v178, v[154:155], off offset:512
	v_add_u32_e32 v162, 0x80, v144
	s_waitcnt lgkmcnt(0)
	v_ashrrev_i32_e32 v163, 31, v162
	v_lshlrev_b64 v[166:167], 10, v[162:163]
	v_lshl_add_u64 v[166:167], v[166:167], 0, v[146:147]
	v_lshlrev_b64 v[174:175], 1, v[166:167]
	v_lshl_add_u64 v[166:167], s[8:9], 0, v[174:175]
	v_lshl_add_u64 v[170:171], s[18:19], 0, v[174:175]
	global_load_dwordx4 v[166:169], v[166:167], off
	v_or_b32_e32 v174, 0x100, v174
	global_load_dwordx4 v[170:173], v[170:171], off
	v_lshl_add_u64 v[176:177], s[18:19], 0, v[174:175]
	s_waitcnt vmcnt(2)
	v_fmamk_f32 v178, v178, 0x3a800000, v193
	v_rsq_f32_e32 v182, v178
	v_lshl_add_u64 v[178:179], s[8:9], 0, v[174:175]
	global_load_dwordx4 v[174:177], v[176:177], off
	s_nop 0
	global_load_dwordx4 v[178:181], v[178:179], off
	v_mul_f32_e32 v182, 0xbfb8aa3b, v182
	v_pk_mul_f32 v[62:63], v[62:63], v[182:183] op_sel_hi:[1,0]
	v_pk_mul_f32 v[60:61], v[60:61], v[182:183] op_sel_hi:[1,0]
	v_pk_mul_f32 v[58:59], v[58:59], v[182:183] op_sel_hi:[1,0]
	v_pk_mul_f32 v[56:57], v[56:57], v[182:183] op_sel_hi:[1,0]
	v_pk_mul_f32 v[48:49], v[48:49], v[182:183] op_sel_hi:[1,0]
	v_exp_f32_e32 v60, v60
	v_exp_f32_e32 v61, v61
	v_exp_f32_e32 v62, v62
	v_exp_f32_e32 v63, v63
	v_exp_f32_e32 v56, v56
	v_exp_f32_e32 v57, v57
	v_exp_f32_e32 v58, v58
	v_exp_f32_e32 v59, v59
	v_exp_f32_e32 v48, v48
	v_exp_f32_e32 v49, v49
	v_pk_mul_f32 v[54:55], v[54:55], v[182:183] op_sel_hi:[1,0]
	v_pk_mul_f32 v[52:53], v[52:53], v[182:183] op_sel_hi:[1,0]
	v_pk_mul_f32 v[50:51], v[50:51], v[182:183] op_sel_hi:[1,0]
	v_exp_f32_e32 v52, v52
	v_exp_f32_e32 v53, v53
	v_exp_f32_e32 v54, v54
	v_exp_f32_e32 v55, v55
	v_exp_f32_e32 v202, v50
	v_exp_f32_e32 v203, v51
	v_add_f32_e32 v50, 1.0, v60
	v_add_f32_e32 v51, 1.0, v61
	v_add_f32_e32 v60, 1.0, v62
	v_add_f32_e32 v61, 1.0, v63
	v_add_f32_e32 v56, 1.0, v56
	v_add_f32_e32 v57, 1.0, v57
	v_add_f32_e32 v58, 1.0, v58
	v_add_f32_e32 v59, 1.0, v59
	v_add_f32_e32 v182, 1.0, v48
	v_add_f32_e32 v183, 1.0, v49
	v_rcp_f32_e32 v48, v50
	v_rcp_f32_e32 v49, v51
	v_rcp_f32_e32 v50, v60
	v_rcp_f32_e32 v51, v61
	v_rcp_f32_e32 v56, v56
	v_rcp_f32_e32 v57, v57
	v_rcp_f32_e32 v58, v58
	v_rcp_f32_e32 v59, v59
	s_waitcnt vmcnt(3)
	v_lshlrev_b32_e32 v184, 16, v166
	v_and_b32_e32 v185, 0xffff0000, v166
	s_waitcnt vmcnt(2)
	v_lshlrev_b32_e32 v196, 16, v170
	v_and_b32_e32 v197, 0xffff0000, v170
	v_lshlrev_b32_e32 v166, 16, v167
	v_and_b32_e32 v167, 0xffff0000, v167
	v_lshlrev_b32_e32 v170, 16, v171
	v_and_b32_e32 v171, 0xffff0000, v171
	v_lshlrev_b32_e32 v198, 16, v168
	v_and_b32_e32 v199, 0xffff0000, v168
	v_lshlrev_b32_e32 v200, 16, v172
	v_and_b32_e32 v201, 0xffff0000, v172
	v_lshlrev_b32_e32 v168, 16, v169
	v_and_b32_e32 v169, 0xffff0000, v169
	v_lshlrev_b32_e32 v172, 16, v173
	v_and_b32_e32 v173, 0xffff0000, v173
	v_add_f32_e32 v52, 1.0, v52
	v_add_f32_e32 v53, 1.0, v53
	v_add_f32_e32 v54, 1.0, v54
	v_add_f32_e32 v55, 1.0, v55
	v_rcp_f32_e32 v60, v52
	v_rcp_f32_e32 v61, v53
	v_rcp_f32_e32 v62, v54
	v_rcp_f32_e32 v63, v55
	v_pk_fma_f32 v[54:55], v[48:49], v[196:197], v[184:185]
	v_pk_fma_f32 v[52:53], v[50:51], v[170:171], v[166:167]
	v_pk_fma_f32 v[50:51], v[56:57], v[200:201], v[198:199]
	v_pk_fma_f32 v[48:49], v[58:59], v[172:173], v[168:169]
	v_pk_mul_f32 v[56:57], v[52:53], v[52:53]
	v_pk_mul_f32 v[58:59], v[54:55], v[54:55]
	v_pk_mul_f32 v[166:167], v[48:49], v[48:49]
	v_pk_mul_f32 v[168:169], v[50:51], v[50:51]
	v_add_f32_e32 v58, v58, v59
	v_add_f32_e32 v56, v56, v57
	v_add_f32_e32 v57, v168, v169
	v_add_f32_e32 v59, v166, v167
	v_add_f32_e32 v56, v58, v56
	v_add_f32_e32 v57, v57, v59
	v_add_f32_e32 v184, v56, v57
	v_add_f32_e32 v56, 1.0, v202
	v_rcp_f32_e32 v182, v182
	v_rcp_f32_e32 v183, v183
	v_rcp_f32_e32 v166, v56
	v_add_f32_e32 v56, 1.0, v203
	v_rcp_f32_e32 v167, v56
	s_waitcnt vmcnt(0)
	v_lshlrev_b32_e32 v56, 16, v178
	v_and_b32_e32 v57, 0xffff0000, v178
	v_lshlrev_b32_e32 v58, 16, v174
	v_and_b32_e32 v59, 0xffff0000, v174
	v_pk_fma_f32 v[56:57], v[60:61], v[58:59], v[56:57]
	v_lshlrev_b32_e32 v58, 16, v179
	v_and_b32_e32 v59, 0xffff0000, v179
	v_lshlrev_b32_e32 v60, 16, v175
	v_and_b32_e32 v61, 0xffff0000, v175
	v_pk_fma_f32 v[58:59], v[62:63], v[60:61], v[58:59]
	v_lshlrev_b32_e32 v60, 16, v180
	v_and_b32_e32 v61, 0xffff0000, v180
	v_lshlrev_b32_e32 v62, 16, v176
	v_and_b32_e32 v63, 0xffff0000, v176
	v_pk_fma_f32 v[60:61], v[182:183], v[62:63], v[60:61]
	v_lshlrev_b32_e32 v62, 16, v181
	v_and_b32_e32 v63, 0xffff0000, v181
	v_lshlrev_b32_e32 v168, 16, v177
	v_and_b32_e32 v169, 0xffff0000, v177
	v_pk_fma_f32 v[62:63], v[166:167], v[168:169], v[62:63]
	v_pk_mul_f32 v[166:167], v[58:59], v[58:59]
	v_pk_mul_f32 v[168:169], v[56:57], v[56:57]
	v_pk_mul_f32 v[170:171], v[62:63], v[62:63]
	v_pk_mul_f32 v[172:173], v[60:61], v[60:61]
	v_add_f32_e32 v168, v168, v169
	v_add_f32_e32 v166, v166, v167
	v_add_f32_e32 v166, v168, v166
	v_add_f32_e32 v167, v172, v173
	v_add_f32_e32 v168, v170, v171
	v_add_f32_e32 v167, v167, v168
	v_add_f32_e32 v166, v166, v167
	v_add_f32_e32 v166, v184, v166
	ds_bpermute_b32 v167, v194, v166
	s_waitcnt lgkmcnt(0)
	v_add_f32_e32 v166, v166, v167
	ds_bpermute_b32 v167, v195, v166
	s_and_saveexec_b64 s[42:43], s[0:1]
	s_cbranch_execz .LBB0_764
	v_lshl_add_u64 v[168:169], v[162:163], 2, s[22:23]
	s_waitcnt lgkmcnt(0)
	v_add_f32_e32 v166, v166, v167
	v_mov_b32_e32 v230, v166
.LBB0_764:
	s_or_b64 exec, exec, s[42:43]
	global_load_dword v180, v[154:155], off offset:576
	v_add_u32_e32 v166, 0x90, v144
	s_waitcnt lgkmcnt(0)
	v_ashrrev_i32_e32 v167, 31, v166
	v_lshlrev_b64 v[168:169], 10, v[166:167]
	v_lshl_add_u64 v[168:169], v[168:169], 0, v[146:147]
	v_lshlrev_b64 v[176:177], 1, v[168:169]
	v_lshl_add_u64 v[168:169], s[8:9], 0, v[176:177]
	v_lshl_add_u64 v[172:173], s[18:19], 0, v[176:177]
	global_load_dwordx4 v[168:171], v[168:169], off
	v_or_b32_e32 v176, 0x100, v176
	global_load_dwordx4 v[172:175], v[172:173], off
	v_lshl_add_u64 v[178:179], s[18:19], 0, v[176:177]
	s_waitcnt vmcnt(2)
	v_fmamk_f32 v180, v180, 0x3a800000, v193
	v_rsq_f32_e32 v184, v180
	v_lshl_add_u64 v[180:181], s[8:9], 0, v[176:177]
	global_load_dwordx4 v[176:179], v[178:179], off
	s_nop 0
	global_load_dwordx4 v[180:183], v[180:181], off
	v_mul_f32_e32 v184, 0xbfb8aa3b, v184
	v_pk_mul_f32 v[46:47], v[46:47], v[184:185] op_sel_hi:[1,0]
	v_pk_mul_f32 v[44:45], v[44:45], v[184:185] op_sel_hi:[1,0]
	v_pk_mul_f32 v[42:43], v[42:43], v[184:185] op_sel_hi:[1,0]
	v_pk_mul_f32 v[40:41], v[40:41], v[184:185] op_sel_hi:[1,0]
	v_pk_mul_f32 v[32:33], v[32:33], v[184:185] op_sel_hi:[1,0]
	v_exp_f32_e32 v44, v44
	v_exp_f32_e32 v45, v45
	v_exp_f32_e32 v46, v46
	v_exp_f32_e32 v47, v47
	v_exp_f32_e32 v40, v40
	v_exp_f32_e32 v41, v41
	v_exp_f32_e32 v42, v42
	v_exp_f32_e32 v43, v43
	v_exp_f32_e32 v32, v32
	v_exp_f32_e32 v33, v33
	v_pk_mul_f32 v[38:39], v[38:39], v[184:185] op_sel_hi:[1,0]
	v_pk_mul_f32 v[36:37], v[36:37], v[184:185] op_sel_hi:[1,0]
	v_pk_mul_f32 v[34:35], v[34:35], v[184:185] op_sel_hi:[1,0]
	v_exp_f32_e32 v36, v36
	v_exp_f32_e32 v37, v37
	v_exp_f32_e32 v38, v38
	v_exp_f32_e32 v39, v39
	v_exp_f32_e32 v204, v34
	v_exp_f32_e32 v205, v35
	v_add_f32_e32 v34, 1.0, v44
	v_add_f32_e32 v35, 1.0, v45
	v_add_f32_e32 v44, 1.0, v46
	v_add_f32_e32 v45, 1.0, v47
	v_add_f32_e32 v40, 1.0, v40
	v_add_f32_e32 v41, 1.0, v41
	v_add_f32_e32 v42, 1.0, v42
	v_add_f32_e32 v43, 1.0, v43
	v_add_f32_e32 v184, 1.0, v32
	v_add_f32_e32 v185, 1.0, v33
	v_rcp_f32_e32 v32, v34
	v_rcp_f32_e32 v33, v35
	v_rcp_f32_e32 v34, v44
	v_rcp_f32_e32 v35, v45
	v_rcp_f32_e32 v40, v40
	v_rcp_f32_e32 v41, v41
	v_rcp_f32_e32 v42, v42
	v_rcp_f32_e32 v43, v43
	s_waitcnt vmcnt(3)
	v_lshlrev_b32_e32 v196, 16, v168
	v_and_b32_e32 v197, 0xffff0000, v168
	s_waitcnt vmcnt(2)
	v_lshlrev_b32_e32 v198, 16, v172
	v_and_b32_e32 v199, 0xffff0000, v172
	v_lshlrev_b32_e32 v168, 16, v169
	v_and_b32_e32 v169, 0xffff0000, v169
	v_lshlrev_b32_e32 v172, 16, v173
	v_and_b32_e32 v173, 0xffff0000, v173
	v_lshlrev_b32_e32 v200, 16, v170
	v_and_b32_e32 v201, 0xffff0000, v170
	v_lshlrev_b32_e32 v202, 16, v174
	v_and_b32_e32 v203, 0xffff0000, v174
	v_lshlrev_b32_e32 v170, 16, v171
	v_and_b32_e32 v171, 0xffff0000, v171
	v_lshlrev_b32_e32 v174, 16, v175
	v_and_b32_e32 v175, 0xffff0000, v175
	v_add_f32_e32 v36, 1.0, v36
	v_add_f32_e32 v37, 1.0, v37
	v_add_f32_e32 v38, 1.0, v38
	v_add_f32_e32 v39, 1.0, v39
	v_rcp_f32_e32 v44, v36
	v_rcp_f32_e32 v45, v37
	v_rcp_f32_e32 v46, v38
	v_rcp_f32_e32 v47, v39
	v_pk_fma_f32 v[38:39], v[32:33], v[198:199], v[196:197]
	v_pk_fma_f32 v[36:37], v[34:35], v[172:173], v[168:169]
	v_pk_fma_f32 v[34:35], v[40:41], v[202:203], v[200:201]
	v_pk_fma_f32 v[32:33], v[42:43], v[174:175], v[170:171]
	v_pk_mul_f32 v[40:41], v[36:37], v[36:37]
	v_pk_mul_f32 v[42:43], v[38:39], v[38:39]
	v_pk_mul_f32 v[168:169], v[32:33], v[32:33]
	v_pk_mul_f32 v[170:171], v[34:35], v[34:35]
	v_add_f32_e32 v42, v42, v43
	v_add_f32_e32 v40, v40, v41
	v_add_f32_e32 v41, v170, v171
	v_add_f32_e32 v43, v168, v169
	v_add_f32_e32 v40, v42, v40
	v_add_f32_e32 v41, v41, v43
	v_add_f32_e32 v196, v40, v41
	v_add_f32_e32 v40, 1.0, v204
	v_rcp_f32_e32 v184, v184
	v_rcp_f32_e32 v185, v185
	v_rcp_f32_e32 v168, v40
	v_add_f32_e32 v40, 1.0, v205
	v_rcp_f32_e32 v169, v40
	s_waitcnt vmcnt(0)
	v_lshlrev_b32_e32 v40, 16, v180
	v_and_b32_e32 v41, 0xffff0000, v180
	v_lshlrev_b32_e32 v42, 16, v176
	v_and_b32_e32 v43, 0xffff0000, v176
	v_pk_fma_f32 v[40:41], v[44:45], v[42:43], v[40:41]
	v_lshlrev_b32_e32 v42, 16, v181
	v_and_b32_e32 v43, 0xffff0000, v181
	v_lshlrev_b32_e32 v44, 16, v177
	v_and_b32_e32 v45, 0xffff0000, v177
	v_pk_fma_f32 v[42:43], v[46:47], v[44:45], v[42:43]
	v_lshlrev_b32_e32 v44, 16, v182
	v_and_b32_e32 v45, 0xffff0000, v182
	v_lshlrev_b32_e32 v46, 16, v178
	v_and_b32_e32 v47, 0xffff0000, v178
	v_pk_fma_f32 v[44:45], v[184:185], v[46:47], v[44:45]
	v_lshlrev_b32_e32 v46, 16, v183
	v_and_b32_e32 v47, 0xffff0000, v183
	v_lshlrev_b32_e32 v170, 16, v179
	v_and_b32_e32 v171, 0xffff0000, v179
	v_pk_fma_f32 v[46:47], v[168:169], v[170:171], v[46:47]
	v_pk_mul_f32 v[168:169], v[42:43], v[42:43]
	v_pk_mul_f32 v[170:171], v[40:41], v[40:41]
	v_pk_mul_f32 v[172:173], v[46:47], v[46:47]
	v_pk_mul_f32 v[174:175], v[44:45], v[44:45]
	v_add_f32_e32 v170, v170, v171
	v_add_f32_e32 v168, v168, v169
	v_add_f32_e32 v168, v170, v168
	v_add_f32_e32 v169, v174, v175
	v_add_f32_e32 v170, v172, v173
	v_add_f32_e32 v169, v169, v170
	v_add_f32_e32 v168, v168, v169
	v_add_f32_e32 v168, v196, v168
	ds_bpermute_b32 v169, v194, v168
	s_waitcnt lgkmcnt(0)
	v_add_f32_e32 v168, v168, v169
	ds_bpermute_b32 v169, v195, v168
	s_and_saveexec_b64 s[42:43], s[0:1]
	s_cbranch_execz .LBB0_766
	v_lshl_add_u64 v[170:171], v[166:167], 2, s[22:23]
	s_waitcnt lgkmcnt(0)
	v_add_f32_e32 v168, v168, v169
	v_mov_b32_e32 v231, v168
.LBB0_766:
	s_or_b64 exec, exec, s[42:43]
	global_load_dword v182, v[154:155], off offset:640
	v_add_u32_e32 v168, 0xa0, v144
	s_waitcnt lgkmcnt(0)
	v_ashrrev_i32_e32 v169, 31, v168
	v_lshlrev_b64 v[170:171], 10, v[168:169]
	v_lshl_add_u64 v[170:171], v[170:171], 0, v[146:147]
	v_lshlrev_b64 v[178:179], 1, v[170:171]
	v_lshl_add_u64 v[170:171], s[8:9], 0, v[178:179]
	v_lshl_add_u64 v[174:175], s[18:19], 0, v[178:179]
	global_load_dwordx4 v[170:173], v[170:171], off
	v_or_b32_e32 v178, 0x100, v178
	global_load_dwordx4 v[174:177], v[174:175], off
	v_lshl_add_u64 v[180:181], s[18:19], 0, v[178:179]
	s_waitcnt vmcnt(2)
	v_fmamk_f32 v182, v182, 0x3a800000, v193
	v_rsq_f32_e32 v196, v182
	v_lshl_add_u64 v[182:183], s[8:9], 0, v[178:179]
	global_load_dwordx4 v[178:181], v[180:181], off
	s_nop 0
	global_load_dwordx4 v[182:185], v[182:183], off
	v_mul_f32_e32 v196, 0xbfb8aa3b, v196
	v_pk_mul_f32 v[30:31], v[30:31], v[196:197] op_sel_hi:[1,0]
	v_pk_mul_f32 v[28:29], v[28:29], v[196:197] op_sel_hi:[1,0]
	v_pk_mul_f32 v[26:27], v[26:27], v[196:197] op_sel_hi:[1,0]
	v_pk_mul_f32 v[24:25], v[24:25], v[196:197] op_sel_hi:[1,0]
	v_pk_mul_f32 v[16:17], v[16:17], v[196:197] op_sel_hi:[1,0]
	v_exp_f32_e32 v28, v28
	v_exp_f32_e32 v29, v29
	v_exp_f32_e32 v30, v30
	v_exp_f32_e32 v31, v31
	v_exp_f32_e32 v24, v24
	v_exp_f32_e32 v25, v25
	v_exp_f32_e32 v26, v26
	v_exp_f32_e32 v27, v27
	v_exp_f32_e32 v16, v16
	v_exp_f32_e32 v17, v17
	v_pk_mul_f32 v[22:23], v[22:23], v[196:197] op_sel_hi:[1,0]
	v_pk_mul_f32 v[20:21], v[20:21], v[196:197] op_sel_hi:[1,0]
	v_pk_mul_f32 v[18:19], v[18:19], v[196:197] op_sel_hi:[1,0]
	v_exp_f32_e32 v20, v20
	v_exp_f32_e32 v21, v21
	v_exp_f32_e32 v22, v22
	v_exp_f32_e32 v23, v23
	v_exp_f32_e32 v206, v18
	v_exp_f32_e32 v207, v19
	v_add_f32_e32 v18, 1.0, v28
	v_add_f32_e32 v19, 1.0, v29
	v_add_f32_e32 v28, 1.0, v30
	v_add_f32_e32 v29, 1.0, v31
	v_add_f32_e32 v24, 1.0, v24
	v_add_f32_e32 v25, 1.0, v25
	v_add_f32_e32 v26, 1.0, v26
	v_add_f32_e32 v27, 1.0, v27
	v_add_f32_e32 v196, 1.0, v16
	v_add_f32_e32 v197, 1.0, v17
	v_rcp_f32_e32 v16, v18
	v_rcp_f32_e32 v17, v19
	v_rcp_f32_e32 v18, v28
	v_rcp_f32_e32 v19, v29
	v_rcp_f32_e32 v24, v24
	v_rcp_f32_e32 v25, v25
	v_rcp_f32_e32 v26, v26
	v_rcp_f32_e32 v27, v27
	s_waitcnt vmcnt(3)
	v_lshlrev_b32_e32 v198, 16, v170
	v_and_b32_e32 v199, 0xffff0000, v170
	s_waitcnt vmcnt(2)
	v_lshlrev_b32_e32 v200, 16, v174
	v_and_b32_e32 v201, 0xffff0000, v174
	v_lshlrev_b32_e32 v170, 16, v171
	v_and_b32_e32 v171, 0xffff0000, v171
	v_lshlrev_b32_e32 v174, 16, v175
	v_and_b32_e32 v175, 0xffff0000, v175
	v_lshlrev_b32_e32 v202, 16, v172
	v_and_b32_e32 v203, 0xffff0000, v172
	v_lshlrev_b32_e32 v204, 16, v176
	v_and_b32_e32 v205, 0xffff0000, v176
	v_lshlrev_b32_e32 v172, 16, v173
	v_and_b32_e32 v173, 0xffff0000, v173
	v_lshlrev_b32_e32 v176, 16, v177
	v_and_b32_e32 v177, 0xffff0000, v177
	v_add_f32_e32 v20, 1.0, v20
	v_add_f32_e32 v21, 1.0, v21
	v_add_f32_e32 v22, 1.0, v22
	v_add_f32_e32 v23, 1.0, v23
	v_rcp_f32_e32 v28, v20
	v_rcp_f32_e32 v29, v21
	v_rcp_f32_e32 v30, v22
	v_rcp_f32_e32 v31, v23
	v_pk_fma_f32 v[22:23], v[16:17], v[200:201], v[198:199]
	v_pk_fma_f32 v[20:21], v[18:19], v[174:175], v[170:171]
	v_pk_fma_f32 v[18:19], v[24:25], v[204:205], v[202:203]
	v_pk_fma_f32 v[16:17], v[26:27], v[176:177], v[172:173]
	v_pk_mul_f32 v[24:25], v[20:21], v[20:21]
	v_pk_mul_f32 v[26:27], v[22:23], v[22:23]
	v_pk_mul_f32 v[170:171], v[16:17], v[16:17]
	v_pk_mul_f32 v[172:173], v[18:19], v[18:19]
	v_add_f32_e32 v26, v26, v27
	v_add_f32_e32 v24, v24, v25
	v_add_f32_e32 v25, v172, v173
	v_add_f32_e32 v27, v170, v171
	v_add_f32_e32 v24, v26, v24
	v_add_f32_e32 v25, v25, v27
	v_add_f32_e32 v198, v24, v25
	v_add_f32_e32 v24, 1.0, v206
	v_rcp_f32_e32 v196, v196
	v_rcp_f32_e32 v197, v197
	v_rcp_f32_e32 v170, v24
	v_add_f32_e32 v24, 1.0, v207
	v_rcp_f32_e32 v171, v24
	s_waitcnt vmcnt(0)
	v_lshlrev_b32_e32 v24, 16, v182
	v_and_b32_e32 v25, 0xffff0000, v182
	v_lshlrev_b32_e32 v26, 16, v178
	v_and_b32_e32 v27, 0xffff0000, v178
	v_pk_fma_f32 v[24:25], v[28:29], v[26:27], v[24:25]
	v_lshlrev_b32_e32 v26, 16, v183
	v_and_b32_e32 v27, 0xffff0000, v183
	v_lshlrev_b32_e32 v28, 16, v179
	v_and_b32_e32 v29, 0xffff0000, v179
	v_pk_fma_f32 v[26:27], v[30:31], v[28:29], v[26:27]
	v_lshlrev_b32_e32 v28, 16, v184
	v_and_b32_e32 v29, 0xffff0000, v184
	v_lshlrev_b32_e32 v30, 16, v180
	v_and_b32_e32 v31, 0xffff0000, v180
	v_pk_fma_f32 v[28:29], v[196:197], v[30:31], v[28:29]
	v_lshlrev_b32_e32 v30, 16, v185
	v_and_b32_e32 v31, 0xffff0000, v185
	v_lshlrev_b32_e32 v172, 16, v181
	v_and_b32_e32 v173, 0xffff0000, v181
	v_pk_fma_f32 v[30:31], v[170:171], v[172:173], v[30:31]
	v_pk_mul_f32 v[170:171], v[26:27], v[26:27]
	v_pk_mul_f32 v[172:173], v[24:25], v[24:25]
	v_pk_mul_f32 v[174:175], v[30:31], v[30:31]
	v_pk_mul_f32 v[176:177], v[28:29], v[28:29]
	v_add_f32_e32 v172, v172, v173
	v_add_f32_e32 v170, v170, v171
	v_add_f32_e32 v170, v172, v170
	v_add_f32_e32 v171, v176, v177
	v_add_f32_e32 v172, v174, v175
	v_add_f32_e32 v171, v171, v172
	v_add_f32_e32 v170, v170, v171
	v_add_f32_e32 v170, v198, v170
	ds_bpermute_b32 v171, v194, v170
	s_waitcnt lgkmcnt(0)
	v_add_f32_e32 v170, v170, v171
	ds_bpermute_b32 v171, v195, v170
	s_and_saveexec_b64 s[42:43], s[0:1]
	s_cbranch_execz .LBB0_768
	v_lshl_add_u64 v[172:173], v[168:169], 2, s[22:23]
	s_waitcnt lgkmcnt(0)
	v_add_f32_e32 v170, v170, v171
	v_mov_b32_e32 v232, v170
.LBB0_768:
	s_or_b64 exec, exec, s[42:43]
	global_load_dword v182, v[154:155], off offset:704
	v_add_u32_e32 v154, 0xb0, v144
	v_ashrrev_i32_e32 v155, 31, v154
	s_waitcnt lgkmcnt(0)
	v_lshlrev_b64 v[170:171], 10, v[154:155]
	v_lshl_add_u64 v[170:171], v[170:171], 0, v[146:147]
	v_lshlrev_b64 v[178:179], 1, v[170:171]
	v_lshl_add_u64 v[170:171], s[8:9], 0, v[178:179]
	v_lshl_add_u64 v[174:175], s[18:19], 0, v[178:179]
	global_load_dwordx4 v[170:173], v[170:171], off
	v_or_b32_e32 v178, 0x100, v178
	global_load_dwordx4 v[174:177], v[174:175], off
	v_lshl_add_u64 v[180:181], s[18:19], 0, v[178:179]
	v_lshl_add_u64 v[178:179], s[8:9], 0, v[178:179]
	s_waitcnt vmcnt(2)
	v_fmamk_f32 v182, v182, 0x3a800000, v193
	v_rsq_f32_e32 v200, v182
	global_load_dwordx4 v[182:185], v[180:181], off
	global_load_dwordx4 v[196:199], v[178:179], off
	v_mul_f32_e32 v178, 0xbfb8aa3b, v200
	v_pk_mul_f32 v[14:15], v[14:15], v[178:179] op_sel_hi:[1,0]
	v_pk_mul_f32 v[12:13], v[12:13], v[178:179] op_sel_hi:[1,0]
	v_pk_mul_f32 v[10:11], v[10:11], v[178:179] op_sel_hi:[1,0]
	v_pk_mul_f32 v[8:9], v[8:9], v[178:179] op_sel_hi:[1,0]
	v_pk_mul_f32 v[6:7], v[6:7], v[178:179] op_sel_hi:[1,0]
	v_pk_mul_f32 v[4:5], v[4:5], v[178:179] op_sel_hi:[1,0]
	v_pk_mul_f32 v[0:1], v[0:1], v[178:179] op_sel_hi:[1,0]
	v_exp_f32_e32 v12, v12
	v_exp_f32_e32 v13, v13
	v_exp_f32_e32 v14, v14
	v_exp_f32_e32 v15, v15
	v_exp_f32_e32 v8, v8
	v_exp_f32_e32 v9, v9
	v_exp_f32_e32 v10, v10
	v_exp_f32_e32 v11, v11
	v_exp_f32_e32 v4, v4
	v_exp_f32_e32 v5, v5
	v_exp_f32_e32 v6, v6
	v_exp_f32_e32 v7, v7
	v_exp_f32_e32 v0, v0
	v_exp_f32_e32 v1, v1
	v_pk_mul_f32 v[2:3], v[2:3], v[178:179] op_sel_hi:[1,0]
	v_add_f32_e32 v8, 1.0, v8
	v_exp_f32_e32 v178, v2
	v_exp_f32_e32 v179, v3
	v_add_f32_e32 v2, 1.0, v12
	v_add_f32_e32 v3, 1.0, v13
	v_add_f32_e32 v12, 1.0, v14
	v_add_f32_e32 v13, 1.0, v15
	v_add_f32_e32 v9, 1.0, v9
	v_add_f32_e32 v10, 1.0, v10
	v_add_f32_e32 v11, 1.0, v11
	s_waitcnt vmcnt(3)
	v_lshlrev_b32_e32 v202, 16, v172
	v_and_b32_e32 v203, 0xffff0000, v172
	s_waitcnt vmcnt(2)
	v_lshlrev_b32_e32 v204, 16, v176
	v_and_b32_e32 v205, 0xffff0000, v176
	v_lshlrev_b32_e32 v206, 16, v173
	v_and_b32_e32 v207, 0xffff0000, v173
	v_lshlrev_b32_e32 v208, 16, v177
	v_and_b32_e32 v209, 0xffff0000, v177
	v_add_f32_e32 v14, 1.0, v4
	v_add_f32_e32 v15, 1.0, v5
	v_add_f32_e32 v172, 1.0, v6
	v_add_f32_e32 v173, 1.0, v7
	v_add_f32_e32 v176, 1.0, v0
	v_add_f32_e32 v177, 1.0, v1
	v_rcp_f32_e32 v0, v2
	v_rcp_f32_e32 v1, v3
	v_rcp_f32_e32 v2, v12
	v_rcp_f32_e32 v3, v13
	v_rcp_f32_e32 v4, v8
	v_rcp_f32_e32 v5, v9
	v_rcp_f32_e32 v6, v10
	v_rcp_f32_e32 v7, v11
	v_lshlrev_b32_e32 v180, 16, v170
	v_and_b32_e32 v181, 0xffff0000, v170
	v_lshlrev_b32_e32 v200, 16, v174
	v_and_b32_e32 v201, 0xffff0000, v174
	v_lshlrev_b32_e32 v170, 16, v171
	v_and_b32_e32 v171, 0xffff0000, v171
	v_lshlrev_b32_e32 v174, 16, v175
	v_and_b32_e32 v175, 0xffff0000, v175
	v_rcp_f32_e32 v10, v172
	v_rcp_f32_e32 v11, v173
	v_rcp_f32_e32 v12, v176
	v_rcp_f32_e32 v13, v177
	v_pk_fma_f32 v[176:177], v[0:1], v[200:201], v[180:181]
	v_pk_fma_f32 v[172:173], v[2:3], v[174:175], v[170:171]
	v_pk_fma_f32 v[174:175], v[4:5], v[204:205], v[202:203]
	v_pk_fma_f32 v[170:171], v[6:7], v[208:209], v[206:207]
	v_pk_mul_f32 v[0:1], v[172:173], v[172:173]
	v_pk_mul_f32 v[2:3], v[176:177], v[176:177]
	v_pk_mul_f32 v[4:5], v[170:171], v[170:171]
	v_pk_mul_f32 v[6:7], v[174:175], v[174:175]
	v_rcp_f32_e32 v8, v14
	v_rcp_f32_e32 v9, v15
	v_add_f32_e32 v2, v2, v3
	v_add_f32_e32 v0, v0, v1
	v_add_f32_e32 v1, v6, v7
	v_add_f32_e32 v3, v4, v5
	v_add_f32_e32 v0, v2, v0
	v_add_f32_e32 v1, v1, v3
	v_add_f32_e32 v14, v0, v1
	v_add_f32_e32 v0, 1.0, v178
	v_add_f32_e32 v1, 1.0, v179
	v_rcp_f32_e32 v0, v0
	v_rcp_f32_e32 v1, v1
	s_waitcnt vmcnt(0)
	v_lshlrev_b32_e32 v2, 16, v196
	v_and_b32_e32 v3, 0xffff0000, v196
	v_lshlrev_b32_e32 v4, 16, v182
	v_and_b32_e32 v5, 0xffff0000, v182
	v_pk_fma_f32 v[178:179], v[8:9], v[4:5], v[2:3]
	v_lshlrev_b32_e32 v2, 16, v197
	v_and_b32_e32 v3, 0xffff0000, v197
	v_lshlrev_b32_e32 v4, 16, v183
	v_and_b32_e32 v5, 0xffff0000, v183
	v_pk_fma_f32 v[180:181], v[10:11], v[4:5], v[2:3]
	v_lshlrev_b32_e32 v2, 16, v198
	v_and_b32_e32 v3, 0xffff0000, v198
	v_lshlrev_b32_e32 v4, 16, v184
	v_and_b32_e32 v5, 0xffff0000, v184
	v_pk_fma_f32 v[182:183], v[12:13], v[4:5], v[2:3]
	v_lshlrev_b32_e32 v2, 16, v199
	v_and_b32_e32 v3, 0xffff0000, v199
	v_lshlrev_b32_e32 v4, 16, v185
	v_and_b32_e32 v5, 0xffff0000, v185
	v_pk_fma_f32 v[184:185], v[0:1], v[4:5], v[2:3]
	v_pk_mul_f32 v[0:1], v[180:181], v[180:181]
	v_pk_mul_f32 v[2:3], v[178:179], v[178:179]
	v_pk_mul_f32 v[4:5], v[184:185], v[184:185]
	v_pk_mul_f32 v[6:7], v[182:183], v[182:183]
	v_add_f32_e32 v2, v2, v3
	v_add_f32_e32 v0, v0, v1
	v_add_f32_e32 v0, v2, v0
	v_add_f32_e32 v1, v6, v7
	v_add_f32_e32 v2, v4, v5
	v_add_f32_e32 v1, v1, v2
	v_add_f32_e32 v0, v0, v1
	v_add_f32_e32 v0, v14, v0
	ds_bpermute_b32 v1, v194, v0
	s_waitcnt lgkmcnt(0)
	v_add_f32_e32 v0, v0, v1
	ds_bpermute_b32 v1, v195, v0
	s_and_saveexec_b64 s[42:43], s[0:1]
	s_cbranch_execz .LBB0_770
	v_lshl_add_u64 v[2:3], v[154:155], 2, s[22:23]
	s_waitcnt lgkmcnt(0)
	v_add_f32_e32 v0, v0, v1
	v_mov_b32_e32 v233, v0
.LBB0_770:
	s_or_b64 exec, exec, s[42:43]
	s_and_saveexec_b64 s[42:43], s[0:1]
	global_atomic_add_f32 v[234:235], v226, off
	global_atomic_add_f32 v[234:235], v227, off offset:64
	global_atomic_add_f32 v[234:235], v228, off offset:128
	global_atomic_add_f32 v[234:235], v229, off offset:192
	global_atomic_add_f32 v[234:235], v230, off offset:512
	global_atomic_add_f32 v[234:235], v231, off offset:576
	global_atomic_add_f32 v[234:235], v232, off offset:640
	global_atomic_add_f32 v[234:235], v233, off offset:704
	s_or_b64 exec, exec, s[42:43]
	s_lshl_b32 s42, s66, 6
	s_ashr_i32 s43, s42, 31
	s_waitcnt vmcnt(0)
	s_lshl_b64 s[42:43], s[42:43], 2
	s_add_u32 s42, s56, s42
	s_addc_u32 s43, s57, s43
	s_and_saveexec_b64 s[44:45], s[6:7]
	s_cbranch_execz .LBB0_773
	s_mov_b64 s[46:47], exec
	v_mbcnt_lo_u32_b32 v0, s46, 0
	v_mbcnt_hi_u32_b32 v0, s47, v0
	v_cmp_eq_u32_e32 vcc, 0, v0
	s_and_b64 s[48:49], exec, vcc
	s_mov_b64 exec, s[48:49]
	s_cbranch_execz .LBB0_773
	s_bcnt1_i32_b64 s37, s[46:47]
	v_mov_b32_e32 v0, s37
	global_atomic_add v131, v0, s[42:43]
